# speedup vs baseline: 1.0183x; 1.0183x over previous
; __device__ __forceinline__ int tidx() { int t = threadIdx.x; asm volatile("" : "+v"(t)); return t; }
; __device__ __forceinline__ float bf2f(bh v) { return __uint_as_float(((unsigned)v) << 16); }
; __device__ __forceinline__ void prep1_phase(const Params& p, int l, int L, bh* __restrict__ U, bh* __restrict__ kb, bh* __restrict__ xc, float* __restrict__ dtb, unsigned* __restrict__ bnd) {
;   const int lane = tidx() & 63, wid = tidx() >> 6;
;   const float* gq = p.in[19] + l * 64; const float* gk = p.in[20] + l * 64;
;   const float* qn = p.in[9] + l * 384; const float* kvn = p.in[10] + l * 256;
;   const float* cw = p.in[13] + l * 3 * 768; const float* cbias = p.in[14] + l * 768;
;   const float* dtbias = p.in[16] + l * 16;
;   float nmax = 0.f; int nseq_cur = -1;
;   for (int t = blockIdx.x * 8 + wid; t < T; t += gridDim.x * 8) {
;     const int pos = t % L;
;     bh* Ur = U + (long)t * UW;
;     {
;       const int sq = t / L;
;       if (sq != nseq_cur) {
;         if (nseq_cur >= 0 && lane < 16) atomicMax(&bnd[(nseq_cur * 8 + (lane & 7)) * 2 + (lane >> 3)], __float_as_uint(nmax));
;         nseq_cur = sq; nmax = 0.f;
;       }
; #pragma unroll
;       for (int j = 0; j < 16; ++j) {
;         const float v = bf2f(Ur[UC_AQ + j * 64 + lane]);
;         const float s2 = wave_sum(v * v);
;         if (lane == j) nmax = fmaxf(nmax, s2);
;       }
;     }
;     for (int hh = 0; hh < 10; ++hh) {
;       const float v = bf2f(Ur[UC_DQ + hh * 64 + lane]);
;       const float ss = wave_sum(v * v);
;       const float gsc = hh < 8 ? gq[lane] : gk[lane];
;       const float vn = v * rsqrtf(ss * (1.f / 64.f) + EPS) * gsc;
;       const float pr = xor16(vn, lane);
;       float c, s; cossin(lane < 32 ? (pos >> 6) : (pos & 63), lane & 15, c, s);
.LBB0_250:
	v_writelane_b32 v253, s20, 59
	s_movk_i32 s72, 0x3fff
	s_or_b64 exec, exec, s[0:1]
	v_readlane_b32 s0, v253, 51
	v_readlane_b32 s1, v253, 52
	s_xor_b64 s[0:1], s[0:1], -1
	v_mov_b32_e32 v3, v188
	v_mov_b32_e32 v1, v188
	v_writelane_b32 v253, s0, 60
	s_barrier
	s_nop 0
	v_writelane_b32 v253, s1, 61
	s_mov_b32 s2, s24
	s_mov_b32 s3, s77
	v_ashrrev_i32_e32 v1, 6, v1
	v_readlane_b32 s0, v252, 49
	v_and_b32_e32 v0, 63, v3
	v_writelane_b32 v253, s2, 62
	v_add_u32_e32 v2, s0, v1
	s_movk_i32 s0, 0x4000
	v_lshlrev_b32_e32 v4, 1, v3
	v_writelane_b32 v253, s3, 63
	s_lshl_b32 s46, s2, 6
	v_cmp_gt_i32_e32 vcc, s0, v2
	v_mov_b32_e32 v102, -1
	v_mov_b32_e32 v103, 0
	v_lshrrev_b32_e32 v1, 3, v0
	v_and_b32_e32 v100, 14, v4
	s_and_saveexec_b64 s[48:49], vcc
	s_mov_b64 s[28:29], 0x100
	s_cbranch_execz .LBB0_314
	v_readlane_b32 s24, v253, 62
	s_mov_b32 s37, s77
	s_mul_i32 s36, s24, 0x300
	v_readlane_b32 s8, v251, 16
	s_lshl_b64 s[0:1], s[36:37], 2
	v_readlane_b32 s20, v251, 28
	v_readlane_b32 s21, v251, 29
	s_add_u32 s0, s20, s0
	s_mul_i32 s36, s24, 0x900
	v_readlane_b32 s18, v251, 26
	s_addc_u32 s1, s21, s1
	s_lshl_b64 s[2:3], s[36:37], 2
	v_readlane_b32 s19, v251, 27
	s_add_u32 s2, s18, s2
	s_addc_u32 s3, s19, s3
	s_lshl_b32 s36, s24, 8
	v_readlane_b32 s12, v251, 20
	s_lshl_b64 s[4:5], s[36:37], 2
	v_readlane_b32 s13, v251, 21
	s_add_u32 s4, s12, s4
	s_mul_i32 s36, s24, 0x180
	v_readlane_b32 s10, v251, 18
	s_addc_u32 s5, s13, s5
	s_lshl_b64 s[6:7], s[36:37], 2
	v_readlane_b32 s11, v251, 19
	s_add_u32 s6, s10, s6
	v_readlane_b32 s25, v253, 63
	v_readlane_b32 s9, v251, 17
	v_readlane_b32 s14, v251, 22
	v_readlane_b32 s15, v251, 23
	v_readlane_b32 s16, v251, 24
	v_readlane_b32 s17, v251, 25
	v_readlane_b32 s22, v251, 30
	v_readlane_b32 s23, v251, 31
	s_addc_u32 s7, s11, s7
	s_lshl_b32 s36, s24, 4
	s_lshl_b64 s[8:9], s[36:37], 2
	v_readlane_b32 s12, v251, 54
	v_readlane_b32 s13, v251, 55
	s_add_u32 s8, s12, s8
	s_addc_u32 s9, s13, s9
	v_and_b32_e32 v4, 15, v3
	v_lshlrev_b32_e32 v4, 3, v4
	s_getpc_b64 s[10:11]
	s_add_u32 s10, s10, _ZL8kFreqRev@rel32@lo+4
	s_addc_u32 s11, s11, _ZL8kFreqRev@rel32@hi+12
	global_load_dwordx2 v[4:5], v4, s[10:11]
	s_waitcnt vmcnt(11)
	v_lshlrev_b32_e32 v18, 2, v0
	v_mov_b32_e32 v19, v177
	v_lshl_add_u64 v[12:13], s[0:1], 0, v[18:19]
	v_readlane_b32 s0, v252, 12
	v_lshlrev_b32_e32 v176, 1, v0
	v_readlane_b32 s1, v252, 13
	v_lshl_add_u64 v[6:7], s[8:9], 0, v[18:19]
	v_lshl_add_u64 v[8:9], s[6:7], 0, v[18:19]
	v_lshl_add_u64 v[16:17], s[0:1], 0, v[176:177]
	v_readlane_b32 s0, v252, 16
	v_readlane_b32 s1, v252, 17
	v_lshl_add_u64 v[10:11], s[4:5], 0, v[18:19]
	v_lshl_add_u64 v[14:15], s[2:3], 0, v[18:19]
	v_lshl_add_u64 v[18:19], s[0:1], 0, v[18:19]
	s_mov_b64 s[0:1], 0x1800
	v_lshl_add_u64 v[20:21], v[14:15], 0, s[0:1]
	s_mov_b64 s[0:1], 0x1900
	s_waitcnt vmcnt(10)
	v_lshl_add_u64 v[24:25], v[14:15], 0, s[0:1]
	s_mov_b64 s[0:1], 0x200
	v_lshl_add_u64 v[26:27], v[14:15], 0, s[0:1]
	s_mov_b64 s[0:1], 0x1a00
	v_lshl_add_u64 v[28:29], v[14:15], 0, s[0:1]
	s_mov_b64 s[0:1], 0x300
	v_lshl_add_u64 v[30:31], v[14:15], 0, s[0:1]
	s_mov_b64 s[0:1], 0x1b00
	s_waitcnt vmcnt(9)
	v_lshl_add_u64 v[32:33], v[14:15], 0, s[0:1]
	s_mov_b64 s[0:1], 0x400
	v_lshl_add_u64 v[34:35], v[14:15], 0, s[0:1]
	s_mov_b64 s[0:1], 0x1c00
	s_waitcnt vmcnt(33)
; __device__ __forceinline__ float bf2f(bh v) { return __uint_as_float(((unsigned)v) << 16); }
; __device__ __forceinline__ bh f2bf(float f) { return (bh)(cvtpk(f, 0.f) & 0xffffu); }
; __device__ __forceinline__ float silu_f(float x) { return x / (1.f + __expf(-x)); }
; __device__ __forceinline__ void prep1_phase(const Params& p, int l, int L, bh* __restrict__ U, bh* __restrict__ kb, bh* __restrict__ xc, float* __restrict__ dtb, unsigned* __restrict__ bnd) {
;     ...
;   const float* gq = p.in[19] + l * 64; const float* gk = p.in[20] + l * 64;
;   const float* qn = p.in[9] + l * 384; const float* kvn = p.in[10] + l * 256;
;   const float* cw = p.in[13] + l * 3 * 768; const float* cbias = p.in[14] + l * 768;
;   const float* dtbias = p.in[16] + l * 16;
;     ...
; #pragma unroll
;       for (int i = 0; i < 6; ++i) { v[i] = bf2f(Ur[UC_CQ + i * 64 + lane]); ss += v[i] * v[i]; }
;       ss = wave_sum(ss);
;       const float r = rsqrtf(ss * (1.f / 384.f) + EPS);
; #pragma unroll
;       for (int i = 0; i < 6; ++i) Ur[UC_CQ + i * 64 + lane] = f2bf(v[i] * r * qn[i * 64 + lane]);
;       float w[4]; ss = 0.f;
; #pragma unroll
;       for (int i = 0; i < 4; ++i) { w[i] = bf2f(Ur[UC_CKV + i * 64 + lane]); ss += w[i] * w[i]; }
;       ss = wave_sum(ss);
;       const float r2 = rsqrtf(ss * (1.f / 256.f) + EPS);
; #pragma unroll
;       for (int i = 0; i < 4; ++i) Ur[UC_CKV + i * 64 + lane] = f2bf(w[i] * r2 * kvn[i * 64 + lane]);
;       const float kv = bf2f(Ur[UC_KR + (lane & 31)]);
;       const float pr = xor16(kv, lane);
;       float c, s; cossin(pos, lane & 15, c, s);
;       float o = (lane & 16) ? (kv * c + pr * s) : (kv * c - pr * s);
;       if (lane >= 32) o = 0.f;
;       const bh ob = f2bf(o);
; #pragma unroll
;       for (int h = 0; h < 4; ++h) kb[(long)t * 512 + h * 128 + 64 + lane] = ob;
;     }
;     {
;       const bool hasL = pos > 0, hasR = pos < L - 1;
; #pragma unroll
;       for (int i = 0; i < 12; ++i) {
;         const int c = i * 64 + lane;
;         float a = cbias[c] + cw[768 + c] * bf2f(Ur[UC_XBC + c]);
;         if (hasL) a += cw[c] * bf2f(Ur[UC_XBC + c - UW]);
;         if (hasR) a += cw[2 * 768 + c] * bf2f(Ur[UC_XBC + c + UW]);
;         xc[(long)t * 768 + c] = f2bf(silu_f(a));
;       }
;     }
;     if (lane < 16) {
;       const float raw = bf2f(Ur[UC_DT + lane]) + dtbias[lane];
	v_lshl_add_u64 v[36:37], v[14:15], 0, s[0:1]
	s_mov_b64 s[0:1], 0x500
	v_lshl_add_u64 v[38:39], v[14:15], 0, s[0:1]
	s_mov_b64 s[0:1], 0x1d00
	v_lshl_add_u64 v[40:41], v[14:15], 0, s[0:1]
	s_mov_b64 s[0:1], 0x600
	v_lshl_add_u64 v[42:43], v[14:15], 0, s[0:1]
	s_mov_b64 s[0:1], 0x1e00
	v_lshl_add_u64 v[44:45], v[14:15], 0, s[0:1]
	s_mov_b64 s[0:1], 0x700
	v_lshl_add_u64 v[46:47], v[14:15], 0, s[0:1]
	s_mov_b64 s[0:1], 0x1f00
	v_lshl_add_u64 v[48:49], v[14:15], 0, s[0:1]
	s_mov_b64 s[0:1], 0x800
	v_lshl_add_u64 v[50:51], v[14:15], 0, s[0:1]
	s_mov_b64 s[0:1], 0x2000
	v_lshl_add_u64 v[52:53], v[14:15], 0, s[0:1]
	s_mov_b64 s[0:1], 0x900
	v_lshl_add_u64 v[54:55], v[14:15], 0, s[0:1]
	s_mov_b64 s[0:1], 0x2100
	v_lshl_add_u64 v[56:57], v[14:15], 0, s[0:1]
	s_mov_b64 s[0:1], 0xa00
	v_lshl_add_u64 v[58:59], v[14:15], 0, s[0:1]
	s_mov_b64 s[0:1], 0x2200
	v_lshl_add_u64 v[60:61], v[14:15], 0, s[0:1]
	s_mov_b64 s[0:1], 0xb00
	v_lshl_add_u64 v[62:63], v[14:15], 0, s[0:1]
	s_mov_b64 s[0:1], 0x2300
	v_lshl_add_u64 v[64:65], v[14:15], 0, s[0:1]
	v_readlane_b32 s0, v252, 53
	v_readlane_b32 s14, v251, 56
	v_readlane_b32 s15, v251, 57
	v_readlane_b32 s16, v251, 58
	v_readlane_b32 s17, v251, 59
	v_readlane_b32 s18, v251, 60
	v_readlane_b32 s19, v251, 61
	v_readlane_b32 s20, v251, 62
	v_readlane_b32 s21, v251, 63
	v_readlane_b32 s22, v252, 0
	v_readlane_b32 s23, v252, 1
	v_readlane_b32 s24, v252, 2
	v_readlane_b32 s25, v252, 3
	v_readlane_b32 s26, v252, 4
	v_readlane_b32 s27, v252, 5
	v_and_b32_e32 v71, 16, v3
	v_and_b32_e32 v70, 31, v3
	v_readlane_b32 s1, v252, 54
	s_mov_b32 s47, s77
	v_add_u32_e32 v101, v100, v1
	v_lshl_add_u64 v[22:23], v[14:15], 0, s[28:29]
	v_lshl_add_u64 v[66:67], s[70:71], 0, v[176:177]
	v_lshl_add_u64 v[68:69], s[0:1], 0, v[176:177]
	v_mov_b32_e32 v102, -1
	v_mov_b32_e32 v103, 0
	v_lshlrev_b32_e32 v70, 1, v70
	v_cmp_gt_u32_e64 s[0:1], 16, v0
	v_cmp_eq_u32_e64 s[2:3], 0, v71
	v_cmp_gt_u32_e64 s[4:5], 32, v0
	v_cmp_lt_u32_e64 s[6:7], 31, v0
	v_cmp_eq_u32_e64 s[8:9], 0, v0
	v_cmp_eq_u32_e64 s[10:11], 1, v0
	v_cmp_eq_u32_e64 s[12:13], 2, v0
	v_cmp_eq_u32_e64 s[14:15], 3, v0
	v_cmp_eq_u32_e64 s[16:17], 4, v0
	v_cmp_eq_u32_e64 s[18:19], 5, v0
	v_cmp_eq_u32_e64 s[20:21], 6, v0
	v_cmp_eq_u32_e64 s[22:23], 7, v0
	v_cmp_eq_u32_e64 s[24:25], 8, v0
	v_cmp_eq_u32_e64 s[26:27], 9, v0
	v_cmp_eq_u32_e64 s[28:29], 10, v0
	v_cmp_eq_u32_e64 s[30:31], 11, v0
	v_cmp_eq_u32_e64 s[34:35], 12, v0
	v_cmp_eq_u32_e64 s[36:37], 13, v0
	v_cmp_eq_u32_e64 s[38:39], 14, v0
	v_cmp_eq_u32_e64 s[40:41], 15, v0
	s_mov_b64 s[50:51], 0
	v_readlane_b32 s58, v251, 60
	v_readlane_b32 s59, v251, 61
	v_readlane_b32 s60, v251, 62
	v_readlane_b32 s61, v251, 63
	v_lshlrev_b32_e32 v238, 2, v0
	s_nop 3
	s_lshl_b64 s[42:43], s[46:47], 2
	s_add_u32 s44, s58, s42
	s_addc_u32 s45, s59, s43
	global_load_dword v239, v238, s[44:45]
	s_add_u32 s52, s60, s42
	s_addc_u32 s53, s61, s43
	global_load_dword v240, v238, s[52:53]
	v_add_co_u32_e32 v232, vcc, 0xc00, v14
	s_nop 1
	v_addc_co_u32_e32 v233, vcc, 0, v15, vcc
	v_add_co_u32_e32 v234, vcc, 0x1800, v14
	s_nop 1
	v_addc_co_u32_e32 v235, vcc, 0, v15, vcc
	global_load_dword v154, v[12:13], off offset:0
	global_load_dword v155, v[12:13], off offset:256
	global_load_dword v156, v[12:13], off offset:512
	global_load_dword v157, v[12:13], off offset:768
	global_load_dword v158, v[12:13], off offset:1024
	global_load_dword v159, v[12:13], off offset:1280
	global_load_dword v160, v[12:13], off offset:1536
	global_load_dword v161, v[12:13], off offset:1792
	global_load_dword v162, v[12:13], off offset:2048
	global_load_dword v163, v[12:13], off offset:2304
	global_load_dword v164, v[12:13], off offset:2560
	global_load_dword v165, v[12:13], off offset:2816
	global_load_dword v166, v[14:15], off offset:0
	global_load_dword v167, v[14:15], off offset:256
	global_load_dword v168, v[14:15], off offset:512
	global_load_dword v169, v[14:15], off offset:768
	global_load_dword v170, v[14:15], off offset:1024
	global_load_dword v171, v[14:15], off offset:1280
	global_load_dword v172, v[14:15], off offset:1536
	global_load_dword v173, v[14:15], off offset:1792
	global_load_dword v174, v[14:15], off offset:2048
	global_load_dword v175, v[14:15], off offset:2304
	global_load_dword v206, v[14:15], off offset:2560
	global_load_dword v207, v[14:15], off offset:2816
	global_load_dword v208, v[232:233], off offset:0
	global_load_dword v209, v[232:233], off offset:256
	global_load_dword v210, v[232:233], off offset:512
	global_load_dword v211, v[232:233], off offset:768
	global_load_dword v212, v[232:233], off offset:1024
	global_load_dword v213, v[232:233], off offset:1280
	global_load_dword v214, v[232:233], off offset:1536
	global_load_dword v215, v[232:233], off offset:1792
	global_load_dword v216, v[232:233], off offset:2048
	global_load_dword v217, v[232:233], off offset:2304
	global_load_dword v218, v[232:233], off offset:2560
	global_load_dword v219, v[232:233], off offset:2816
	global_load_dword v220, v[234:235], off offset:0
	global_load_dword v221, v[234:235], off offset:256
	global_load_dword v222, v[234:235], off offset:512
	global_load_dword v223, v[234:235], off offset:768
	global_load_dword v224, v[234:235], off offset:1024
	global_load_dword v225, v[234:235], off offset:1280
	global_load_dword v226, v[234:235], off offset:1536
	global_load_dword v227, v[234:235], off offset:1792
	global_load_dword v228, v[234:235], off offset:2048
	global_load_dword v229, v[234:235], off offset:2304
	global_load_dword v230, v[234:235], off offset:2560
	global_load_dword v231, v[234:235], off offset:2816
	global_load_dword v182, v[8:9], off
	global_load_dword v183, v[8:9], off offset:256
	global_load_dword v184, v[8:9], off offset:512
	global_load_dword v185, v[8:9], off offset:768
	global_load_dword v232, v[8:9], off offset:1024
	global_load_dword v233, v[8:9], off offset:1280
	global_load_dword v234, v[10:11], off
	global_load_dword v235, v[10:11], off offset:256
	global_load_dword v238, v[10:11], off offset:512
	global_load_dword v241, v[10:11], off offset:768
	s_mov_b64 s[42:43], exec
	s_and_b64 exec, exec, s[0:1]
	global_load_dword v187, v[6:7], off
	s_mov_b64 exec, s[42:43]
	s_branch .LBB0_254

; __device__ __forceinline__ float bf2f(bh v) { return __uint_as_float(((unsigned)v) << 16); }
; __device__ __forceinline__ bh f2bf(float f) { return (bh)(cvtpk(f, 0.f) & 0xffffu); }
; __device__ __forceinline__ void prep1_phase(const Params& p, int l, int L, bh* __restrict__ U, bh* __restrict__ kb, bh* __restrict__ xc, float* __restrict__ dtb, unsigned* __restrict__ bnd) {
;     ...
;     for (int hh = 0; hh < 10; ++hh) {
;       const float v = bf2f(Ur[UC_DQ + hh * 64 + lane]);
;       const float ss = wave_sum(v * v);
;       const float gsc = hh < 8 ? gq[lane] : gk[lane];
;       const float vn = v * rsqrtf(ss * (1.f / 64.f) + EPS) * gsc;
;       const float pr = xor16(vn, lane);
;       float c, s; cossin(lane < 32 ? (pos >> 6) : (pos & 63), lane & 15, c, s);
;       const float o = (lane & 16) ? (vn * c + pr * s) : (vn * c - pr * s);
;       Ur[UC_DQ + hh * 64 + lane] = f2bf(o);
;     }
;     {
;       float v[6]; float ss = 0.f;
; #pragma unroll
;       for (int i = 0; i < 6; ++i) { v[i] = bf2f(Ur[UC_CQ + i * 64 + lane]); ss += v[i] * v[i]; }
;       ss = wave_sum(ss);
;       const float r = rsqrtf(ss * (1.f / 384.f) + EPS);
; #pragma unroll
;       for (int i = 0; i < 6; ++i) Ur[UC_CQ + i * 64 + lane] = f2bf(v[i] * r * qn[i * 64 + lane]);
;       float w[4]; ss = 0.f;
; #pragma unroll
;       for (int i = 0; i < 4; ++i) { w[i] = bf2f(Ur[UC_CKV + i * 64 + lane]); ss += w[i] * w[i]; }
;       ss = wave_sum(ss);
;       const float r2 = rsqrtf(ss * (1.f / 256.f) + EPS);
; #pragma unroll
;       for (int i = 0; i < 4; ++i) Ur[UC_CKV + i * 64 + lane] = f2bf(w[i] * r2 * kvn[i * 64 + lane]);
;       const float kv = bf2f(Ur[UC_KR + (lane & 31)]);
.LBB0_259:
	v_mov_b32_e32 v242, v244
	v_mov_b32_e32 v243, v245
	global_load_ushort v244, v[98:99], off offset:128
	global_load_ushort v245, v[98:99], off offset:256
	s_cmp_lt_u32 s33, 8
	s_cselect_b64 s[44:45], -1, 0
	s_add_i32 s33, s33, 2
	s_cmp_lg_u32 s33, 10
	v_lshlrev_b32_e32 v242, 16, v242
	v_mul_f32_e32 v139, v242, v242
	s_nop 1
	v_mov_b32_dpp v139, v139 quad_perm:[1,0,3,2] row_mask:0xf bank_mask:0xf bound_ctrl:1
	v_fmac_f32_e32 v139, v242, v242
	s_nop 1
	v_add_f32_dpp v139, v139, v139 quad_perm:[2,3,0,1] row_mask:0xf bank_mask:0xf bound_ctrl:1
	s_nop 1
	v_add_f32_dpp v139, v139, v139 row_half_mirror row_mask:0xf bank_mask:0xf bound_ctrl:1
	s_nop 1
	v_add_f32_dpp v139, v139, v139 row_mirror row_mask:0xf bank_mask:0xf bound_ctrl:1
	v_mov_b32_e32 v140, v139
	s_nop 1
	v_permlane16_swap_b32_e32 v139, v140
	v_add_f32_e32 v139, v139, v140
	v_mov_b32_e32 v140, v139
	s_nop 1
	v_permlane32_swap_b32_e32 v139, v140
	v_add_f32_e32 v139, v139, v140
	v_cndmask_b32_e64 v140, v240, v239, s[44:45]
	v_fmamk_f32 v139, v139, 0x3c800000, v189
	v_cmp_gt_f32_e32 vcc, s52, v139
	v_mul_f32_e32 v141, 0x4b800000, v139
	s_nop 0
	v_cndmask_b32_e32 v139, v139, v141, vcc
	v_rsq_f32_e32 v139, v139
	s_nop 0
	v_mul_f32_e32 v141, 0x45800000, v139
	v_cndmask_b32_e32 v139, v139, v141, vcc
	v_mul_f32_e32 v242, v139, v242
	v_mul_f32_e32 v242, v140, v242
	v_mov_b32_e32 v139, v242
	v_mov_b32_e32 v141, v242
	s_nop 1
	v_permlane16_swap_b32_e32 v139, v141
	v_cndmask_b32_e64 v139, v139, v141, s[2:3]
	v_mul_f32_e32 v139, v137, v139
	v_cndmask_b32_e64 v139, v139, -v139, s[2:3]
	v_fmac_f32_e32 v139, v71, v242
	v_cvt_pk_bf16_f32 v242, v139, v177
	global_store_short v[98:99], v242, off offset:-128
	v_lshlrev_b32_e32 v243, 16, v243
	v_mul_f32_e32 v139, v243, v243
	s_nop 1
	v_mov_b32_dpp v139, v139 quad_perm:[1,0,3,2] row_mask:0xf bank_mask:0xf bound_ctrl:1
	v_fmac_f32_e32 v139, v243, v243
	s_nop 1
	v_add_f32_dpp v139, v139, v139 quad_perm:[2,3,0,1] row_mask:0xf bank_mask:0xf bound_ctrl:1
	s_nop 1
	v_add_f32_dpp v139, v139, v139 row_half_mirror row_mask:0xf bank_mask:0xf bound_ctrl:1
	s_nop 1
	v_add_f32_dpp v139, v139, v139 row_mirror row_mask:0xf bank_mask:0xf bound_ctrl:1
	v_mov_b32_e32 v141, v139
	s_nop 1
	v_permlane16_swap_b32_e32 v139, v141
	v_add_f32_e32 v139, v139, v141
	v_mov_b32_e32 v141, v139
	s_nop 1
	v_permlane32_swap_b32_e32 v139, v141
	v_add_f32_e32 v139, v139, v141
	v_fmamk_f32 v139, v139, 0x3c800000, v189
	v_cmp_gt_f32_e32 vcc, s52, v139
	v_mul_f32_e32 v141, 0x4b800000, v139
	s_nop 0
	v_cndmask_b32_e32 v139, v139, v141, vcc
	v_rsq_f32_e32 v139, v139
	s_nop 0
	v_mul_f32_e32 v141, 0x45800000, v139
	v_cndmask_b32_e32 v139, v139, v141, vcc
	v_mul_f32_e32 v243, v139, v243
	v_mul_f32_e32 v243, v140, v243
	v_mov_b32_e32 v139, v243
	v_mov_b32_e32 v140, v243
	s_nop 1
	v_permlane16_swap_b32_e32 v139, v140
	v_cndmask_b32_e64 v139, v139, v140, s[2:3]
	v_mul_f32_e32 v139, v137, v139
	v_cndmask_b32_e64 v139, v139, -v139, s[2:3]
	v_fmac_f32_e32 v139, v71, v243
	v_cvt_pk_bf16_f32 v243, v139, v177
	global_store_short v[98:99], v243, off
	v_lshl_add_u64 v[98:99], v[98:99], 0, s[78:79]
	s_waitcnt vmcnt(2)
	s_cbranch_scc1 .LBB0_259
	global_load_ushort v71, v[72:73], off offset:3072
	global_load_ushort v98, v[72:73], off offset:3200
	global_load_ushort v137, v[72:73], off offset:3328
	global_load_ushort v138, v[72:73], off offset:3456
	global_load_ushort v139, v[72:73], off offset:3584
	global_load_ushort v140, v[72:73], off offset:3712
	s_movk_i32 s33, 0x1000
	v_cmp_lt_i32_e64 s[42:43], 0, v136
	global_load_ushort v76, v[72:73], off offset:3840
	global_load_ushort v77, v[72:73], off offset:3968
	v_add_co_u32_e32 v74, vcc, s33, v72
	v_mov_b32_e32 v82, v70
	v_mov_b32_e32 v83, 0
	v_addc_co_u32_e32 v75, vcc, 0, v73, vcc
	v_lshl_add_u64 v[80:81], v[96:97], 0, v[82:83]
	global_load_ushort v78, v[74:75], off
	global_load_ushort v79, v[74:75], off offset:128
	v_add_co_u32_e32 v80, vcc, s33, v80
	global_load_ushort v186, v[74:75], off offset:2880
	v_addc_co_u32_e32 v81, vcc, 0, v81, vcc
	global_load_ushort v84, v[80:81], off offset:256
	s_waitcnt vmcnt(11)
	v_lshlrev_b32_e32 v71, 16, v71
	s_waitcnt vmcnt(10)
	v_lshlrev_b32_e32 v98, 16, v98
	v_mul_f32_e32 v99, v98, v98
	v_fmac_f32_e32 v99, v71, v71
	s_waitcnt vmcnt(9)
	v_lshlrev_b32_e32 v137, 16, v137
	v_fmac_f32_e32 v99, v137, v137
	s_waitcnt vmcnt(8)
	v_lshlrev_b32_e32 v138, 16, v138
	v_fmac_f32_e32 v99, v138, v138
	s_waitcnt vmcnt(7)
	v_lshlrev_b32_e32 v139, 16, v139
	v_fmac_f32_e32 v99, v139, v139
	s_waitcnt vmcnt(6)
	v_lshlrev_b32_e32 v140, 16, v140
	v_fmac_f32_e32 v99, v140, v140
	s_nop 1
	v_add_f32_dpp v99, v99, v99 quad_perm:[1,0,3,2] row_mask:0xf bank_mask:0xf bound_ctrl:1
	s_nop 1
	v_add_f32_dpp v99, v99, v99 quad_perm:[2,3,0,1] row_mask:0xf bank_mask:0xf bound_ctrl:1
	s_nop 1
	v_add_f32_dpp v99, v99, v99 row_half_mirror row_mask:0xf bank_mask:0xf bound_ctrl:1
	s_nop 1
	v_add_f32_dpp v99, v99, v99 row_mirror row_mask:0xf bank_mask:0xf bound_ctrl:1
	v_mov_b32_e32 v141, v99
	s_nop 1
	v_permlane16_swap_b32_e32 v99, v141
	v_add_f32_e32 v99, v99, v141
	v_mov_b32_e32 v141, v99
	s_nop 1
	v_permlane32_swap_b32_e32 v99, v141
	v_add_f32_e32 v99, v99, v141
	v_fmamk_f32 v99, v99, 0x3b2aaaab, v189
	v_cmp_gt_f32_e32 vcc, s52, v99
	v_mul_f32_e32 v141, 0x4b800000, v99
	s_nop 0
	v_cndmask_b32_e32 v99, v99, v141, vcc
	v_rsq_f32_e32 v99, v99
	s_nop 0
	v_mul_f32_e32 v141, 0x45800000, v99
	v_cndmask_b32_e32 v99, v99, v141, vcc
	v_mul_f32_e32 v71, v99, v71
	v_mul_f32_e32 v71, v182, v71
	v_cvt_pk_bf16_f32 v71, v71, v177
	global_store_short v[72:73], v71, off offset:3072
	v_mul_f32_e32 v71, v99, v98
	v_mul_f32_e32 v71, v183, v71
	v_cvt_pk_bf16_f32 v71, v71, v177
	global_store_short v[72:73], v71, off offset:3200
	v_mul_f32_e32 v71, v99, v137
	v_mul_f32_e32 v71, v184, v71
	v_cvt_pk_bf16_f32 v71, v71, v177
	global_store_short v[72:73], v71, off offset:3328
	v_mul_f32_e32 v71, v99, v138
	v_mul_f32_e32 v71, v185, v71
	v_cvt_pk_bf16_f32 v71, v71, v177
	global_store_short v[72:73], v71, off offset:3456
	v_mul_f32_e32 v71, v99, v139
	v_mul_f32_e32 v71, v71, v232
	v_cvt_pk_bf16_f32 v71, v71, v177
	global_store_short v[72:73], v71, off offset:3584
	v_mul_f32_e32 v71, v99, v140
	v_mul_f32_e32 v71, v71, v233
	v_cvt_pk_bf16_f32 v71, v71, v177
	global_store_short v[72:73], v71, off offset:3712
	s_waitcnt vmcnt(6)
; __device__ __forceinline__ float bf2f(bh v) { return __uint_as_float(((unsigned)v) << 16); }
; __device__ __forceinline__ bh f2bf(float f) { return (bh)(cvtpk(f, 0.f) & 0xffffu); }
; __device__ __forceinline__ float silu_f(float x) { return x / (1.f + __expf(-x)); }
; __device__ __forceinline__ void prep1_phase(const Params& p, int l, int L, bh* __restrict__ U, bh* __restrict__ kb, bh* __restrict__ xc, float* __restrict__ dtb, unsigned* __restrict__ bnd) {
;     ...
;       float w[4]; ss = 0.f;
; #pragma unroll
;       for (int i = 0; i < 4; ++i) { w[i] = bf2f(Ur[UC_CKV + i * 64 + lane]); ss += w[i] * w[i]; }
;       ss = wave_sum(ss);
;       const float r2 = rsqrtf(ss * (1.f / 256.f) + EPS);
; #pragma unroll
;       for (int i = 0; i < 4; ++i) Ur[UC_CKV + i * 64 + lane] = f2bf(w[i] * r2 * kvn[i * 64 + lane]);
;       const float kv = bf2f(Ur[UC_KR + (lane & 31)]);
;       const float pr = xor16(kv, lane);
;       float c, s; cossin(pos, lane & 15, c, s);
;       float o = (lane & 16) ? (kv * c + pr * s) : (kv * c - pr * s);
;       if (lane >= 32) o = 0.f;
;       const bh ob = f2bf(o);
; #pragma unroll
;       for (int h = 0; h < 4; ++h) kb[(long)t * 512 + h * 128 + 64 + lane] = ob;
;     }
;     {
;       const bool hasL = pos > 0, hasR = pos < L - 1;
; #pragma unroll
;       for (int i = 0; i < 12; ++i) {
;         const int c = i * 64 + lane;
;         float a = cbias[c] + cw[768 + c] * bf2f(Ur[UC_XBC + c]);
;         if (hasL) a += cw[c] * bf2f(Ur[UC_XBC + c - UW]);
;         if (hasR) a += cw[2 * 768 + c] * bf2f(Ur[UC_XBC + c + UW]);
;         xc[(long)t * 768 + c] = f2bf(silu_f(a));
	v_mov_b32_e32 v71, v76
	s_nop 0
	v_mov_b32_e32 v98, v77
	v_lshlrev_b32_e32 v71, 16, v71
	v_lshlrev_b32_e32 v137, 16, v98
	v_add_co_u32_e32 v98, vcc, s33, v72
	v_mul_f32_e32 v138, v137, v137
	s_nop 0
	v_addc_co_u32_e32 v99, vcc, 0, v73, vcc
	v_mov_b32_e32 v139, v78
	v_mov_b32_e32 v140, v79
	v_fmac_f32_e32 v138, v71, v71
	v_lshlrev_b32_e32 v139, 16, v139
	v_fmac_f32_e32 v138, v139, v139
	v_lshlrev_b32_e32 v140, 16, v140
	v_fmac_f32_e32 v138, v140, v140
	s_nop 1
	v_add_f32_dpp v138, v138, v138 quad_perm:[1,0,3,2] row_mask:0xf bank_mask:0xf bound_ctrl:1
	s_nop 1
	v_add_f32_dpp v138, v138, v138 quad_perm:[2,3,0,1] row_mask:0xf bank_mask:0xf bound_ctrl:1
	s_nop 1
	v_add_f32_dpp v138, v138, v138 row_half_mirror row_mask:0xf bank_mask:0xf bound_ctrl:1
	s_nop 1
	v_add_f32_dpp v138, v138, v138 row_mirror row_mask:0xf bank_mask:0xf bound_ctrl:1
	v_mov_b32_e32 v141, v138
	s_nop 1
	v_permlane16_swap_b32_e32 v138, v141
	v_add_f32_e32 v138, v138, v141
	v_mov_b32_e32 v141, v138
	s_nop 1
	v_permlane32_swap_b32_e32 v138, v141
	v_add_f32_e32 v138, v138, v141
	v_fmamk_f32 v138, v138, 0x3b800000, v189
	v_cmp_gt_f32_e32 vcc, s52, v138
	v_mul_f32_e32 v141, 0x4b800000, v138
	s_nop 0
	v_cndmask_b32_e32 v138, v138, v141, vcc
	v_rsq_f32_e32 v138, v138
	s_nop 0
	v_mul_f32_e32 v141, 0x45800000, v138
	v_cndmask_b32_e32 v138, v138, v141, vcc
	v_mul_f32_e32 v71, v138, v71
	v_mul_f32_e32 v71, v234, v71
	v_cvt_pk_bf16_f32 v71, v71, v177
	global_store_short v[72:73], v71, off offset:3840
	v_mul_f32_e32 v71, v138, v137
	v_mul_f32_e32 v71, v235, v71
	v_cvt_pk_bf16_f32 v71, v71, v177
	global_store_short v[72:73], v71, off offset:3968
	v_mul_f32_e32 v71, v138, v139
	v_mul_f32_e32 v71, v238, v71
	v_cvt_pk_bf16_f32 v71, v71, v177
	global_store_short v[98:99], v71, off
	v_mul_f32_e32 v71, v138, v140
	v_mul_f32_e32 v71, v241, v71
	v_cvt_pk_bf16_f32 v71, v71, v177
	global_store_short v[98:99], v71, off offset:128
	v_mov_b32_e32 v71, v177
	v_lshl_add_u64 v[96:97], v[96:97], 0, v[70:71]
	v_add_co_u32_e32 v96, vcc, s33, v96
	s_nop 1
	v_addc_co_u32_e32 v97, vcc, 0, v97, vcc
	v_mov_b32_e32 v71, v84
	v_lshlrev_b32_e32 v71, 16, v71
	v_mov_b32_e32 v96, v71
	v_mov_b32_e32 v97, v71
	s_nop 1
	v_permlane16_swap_b32_e32 v96, v97
	v_cndmask_b32_e64 v137, v96, v97, s[2:3]
	v_cvt_f64_i32_e32 v[96:97], v136
	v_mul_f64 v[138:139], v[4:5], v[96:97]
	v_floor_f64_e32 v[138:139], v[138:139]
	v_fma_f64 v[96:97], v[4:5], v[96:97], -v[138:139]
	v_cvt_f32_f64_e32 v96, v[96:97]
	v_cos_f32_e32 v97, v96
	v_sin_f32_e32 v96, v96
	s_nop 0
	v_mul_f32_e32 v96, v96, v137
	v_cndmask_b32_e64 v96, v96, -v96, s[2:3]
	v_fmac_f32_e32 v96, v97, v71
	v_cndmask_b32_e64 v71, v96, 0, s[6:7]
	v_lshlrev_b64 v[96:97], 10, v[2:3]
	v_cvt_pk_bf16_f32 v71, v71, v177
	v_lshl_add_u64 v[96:97], v[16:17], 0, v[96:97]
	global_store_short v[96:97], v71, off offset:128
	global_store_short v[96:97], v71, off offset:384
	global_store_short v[96:97], v71, off offset:640
	global_store_short v[96:97], v71, off offset:896
	v_readlane_b32 s33, v253, 53
	v_mov_b32_e32 v138, 0xffffde00
	v_mov_b32_e32 v140, 0x2200
	v_mov_b32_e32 v141, 0
	v_cndmask_b32_e64 v138, 0, v138, s[42:43]
	v_cmp_gt_i32_e64 s[44:45], s33, v136
	v_ashrrev_i32_e32 v139, 31, v138
	v_lshl_add_u64 v[138:139], v[98:99], 0, v[138:139]
	v_mad_i64_i32 v[236:237], s[52:53], v2, s74, v[66:67]
	v_cndmask_b32_e64 v140, 0, v140, s[44:45]
	s_nop 0
	v_lshl_add_u64 v[140:141], v[98:99], 0, v[140:141]
	global_load_ushort v74, v[98:99], off offset:1344
	global_load_ushort v75, v[98:99], off offset:1472
	global_load_ushort v76, v[98:99], off offset:1600
	global_load_ushort v77, v[98:99], off offset:1728
	global_load_ushort v78, v[98:99], off offset:1856
	global_load_ushort v79, v[98:99], off offset:1984
	global_load_ushort v80, v[98:99], off offset:2112
	global_load_ushort v81, v[98:99], off offset:2240
	global_load_ushort v82, v[98:99], off offset:2368
	global_load_ushort v83, v[98:99], off offset:2496
	global_load_ushort v84, v[98:99], off offset:2624
	global_load_ushort v85, v[98:99], off offset:2752
	global_load_ushort v86, v[138:139], off offset:1344
	global_load_ushort v87, v[138:139], off offset:1472
	global_load_ushort v88, v[138:139], off offset:1600
	global_load_ushort v89, v[138:139], off offset:1728
	global_load_ushort v90, v[138:139], off offset:1856
	global_load_ushort v91, v[138:139], off offset:1984
	global_load_ushort v92, v[138:139], off offset:2112
	global_load_ushort v93, v[138:139], off offset:2240
	global_load_ushort v94, v[138:139], off offset:2368
	global_load_ushort v95, v[138:139], off offset:2496
	global_load_ushort v96, v[138:139], off offset:2624
	global_load_ushort v97, v[138:139], off offset:2752
	global_load_ushort v142, v[140:141], off offset:1344
	global_load_ushort v143, v[140:141], off offset:1472
	global_load_ushort v144, v[140:141], off offset:1600
	global_load_ushort v145, v[140:141], off offset:1728
	global_load_ushort v146, v[140:141], off offset:1856
	global_load_ushort v147, v[140:141], off offset:1984
	global_load_ushort v148, v[140:141], off offset:2112
	global_load_ushort v149, v[140:141], off offset:2240
	global_load_ushort v150, v[140:141], off offset:2368
	global_load_ushort v151, v[140:141], off offset:2496
	global_load_ushort v152, v[140:141], off offset:2624
	global_load_ushort v153, v[140:141], off offset:2752
	s_waitcnt vmcnt(11)
; __device__ __forceinline__ float bf2f(bh v) { return __uint_as_float(((unsigned)v) << 16); }
; __device__ __forceinline__ bh f2bf(float f) { return (bh)(cvtpk(f, 0.f) & 0xffffu); }
; __device__ __forceinline__ float silu_f(float x) { return x / (1.f + __expf(-x)); }
; __device__ __forceinline__ void prep1_phase(const Params& p, int l, int L, bh* __restrict__ U, bh* __restrict__ kb, bh* __restrict__ xc, float* __restrict__ dtb, unsigned* __restrict__ bnd) {
;     ...
;       const bool hasL = pos > 0, hasR = pos < L - 1;
; #pragma unroll
;       for (int i = 0; i < 12; ++i) {
;         const int c = i * 64 + lane;
;         float a = cbias[c] + cw[768 + c] * bf2f(Ur[UC_XBC + c]);
;         if (hasL) a += cw[c] * bf2f(Ur[UC_XBC + c - UW]);
;         if (hasR) a += cw[2 * 768 + c] * bf2f(Ur[UC_XBC + c + UW]);
;         xc[(long)t * 768 + c] = f2bf(silu_f(a));
;       }
	v_lshlrev_b32_e32 v98, 16, v74
	v_fma_f32 v71, v208, v98, v154
	v_lshlrev_b32_e32 v98, 16, v86
	v_lshlrev_b32_e32 v99, 16, v142
	v_cndmask_b32_e64 v98, 0, v98, s[42:43]
	v_cndmask_b32_e64 v99, 0, v99, s[44:45]
	v_fmac_f32_e32 v71, v166, v98
	v_fmac_f32_e32 v71, v220, v99
	v_mul_f32_e32 v98, 0xbfb8aa3b, v71
	v_exp_f32_e32 v98, v98
	s_nop 0
	v_add_f32_e32 v99, 1.0, v98
	v_div_scale_f32 v98, s[52:53], v99, v99, v71
	v_rcp_f32_e32 v137, v98
	v_div_scale_f32 v136, vcc, v71, v99, v71
	v_fma_f32 v139, -v98, v137, 1.0
	v_fmac_f32_e32 v137, v139, v137
	v_mul_f32_e32 v139, v136, v137
	v_fma_f32 v140, -v98, v139, v136
	v_fmac_f32_e32 v139, v140, v137
	v_fma_f32 v98, -v98, v139, v136
	v_div_fmas_f32 v136, v98, v137, v139
	v_div_fixup_f32 v71, v136, v99, v71
	v_cvt_pk_bf16_f32 v71, v71, v177
	global_store_short v[236:237], v71, off offset:0
	s_waitcnt vmcnt(11)
	v_lshlrev_b32_e32 v98, 16, v75
	v_fma_f32 v71, v209, v98, v155
	v_lshlrev_b32_e32 v98, 16, v87
	v_lshlrev_b32_e32 v99, 16, v143
	v_cndmask_b32_e64 v98, 0, v98, s[42:43]
	v_cndmask_b32_e64 v99, 0, v99, s[44:45]
	v_fmac_f32_e32 v71, v167, v98
	v_fmac_f32_e32 v71, v221, v99
	v_mul_f32_e32 v98, 0xbfb8aa3b, v71
	v_exp_f32_e32 v98, v98
	s_nop 0
	v_add_f32_e32 v99, 1.0, v98
	v_div_scale_f32 v98, s[52:53], v99, v99, v71
	v_rcp_f32_e32 v137, v98
	v_div_scale_f32 v136, vcc, v71, v99, v71
	v_fma_f32 v139, -v98, v137, 1.0
	v_fmac_f32_e32 v137, v139, v137
	v_mul_f32_e32 v139, v136, v137
	v_fma_f32 v140, -v98, v139, v136
	v_fmac_f32_e32 v139, v140, v137
	v_fma_f32 v98, -v98, v139, v136
	v_div_fmas_f32 v136, v98, v137, v139
	v_div_fixup_f32 v71, v136, v99, v71
	v_cvt_pk_bf16_f32 v71, v71, v177
	global_store_short v[236:237], v71, off offset:128
	s_waitcnt vmcnt(11)
	v_lshlrev_b32_e32 v98, 16, v76
	v_fma_f32 v71, v210, v98, v156
	v_lshlrev_b32_e32 v98, 16, v88
	v_lshlrev_b32_e32 v99, 16, v144
	v_cndmask_b32_e64 v98, 0, v98, s[42:43]
	v_cndmask_b32_e64 v99, 0, v99, s[44:45]
	v_fmac_f32_e32 v71, v168, v98
	v_fmac_f32_e32 v71, v222, v99
	v_mul_f32_e32 v98, 0xbfb8aa3b, v71
	v_exp_f32_e32 v98, v98
	s_nop 0
	v_add_f32_e32 v99, 1.0, v98
	v_div_scale_f32 v98, s[52:53], v99, v99, v71
	v_rcp_f32_e32 v137, v98
	v_div_scale_f32 v136, vcc, v71, v99, v71
	v_fma_f32 v139, -v98, v137, 1.0
	v_fmac_f32_e32 v137, v139, v137
	v_mul_f32_e32 v139, v136, v137
	v_fma_f32 v140, -v98, v139, v136
	v_fmac_f32_e32 v139, v140, v137
	v_fma_f32 v98, -v98, v139, v136
	v_div_fmas_f32 v136, v98, v137, v139
	v_div_fixup_f32 v71, v136, v99, v71
	v_cvt_pk_bf16_f32 v71, v71, v177
	global_store_short v[236:237], v71, off offset:256
	s_waitcnt vmcnt(11)
	v_lshlrev_b32_e32 v98, 16, v77
	v_fma_f32 v71, v211, v98, v157
	v_lshlrev_b32_e32 v98, 16, v89
	v_lshlrev_b32_e32 v99, 16, v145
	v_cndmask_b32_e64 v98, 0, v98, s[42:43]
	v_cndmask_b32_e64 v99, 0, v99, s[44:45]
	v_fmac_f32_e32 v71, v169, v98
	v_fmac_f32_e32 v71, v223, v99
	v_mul_f32_e32 v98, 0xbfb8aa3b, v71
	v_exp_f32_e32 v98, v98
	s_nop 0
	v_add_f32_e32 v99, 1.0, v98
	v_div_scale_f32 v98, s[52:53], v99, v99, v71
	v_rcp_f32_e32 v137, v98
	v_div_scale_f32 v136, vcc, v71, v99, v71
	v_fma_f32 v139, -v98, v137, 1.0
	v_fmac_f32_e32 v137, v139, v137
	v_mul_f32_e32 v139, v136, v137
	v_fma_f32 v140, -v98, v139, v136
	v_fmac_f32_e32 v139, v140, v137
	v_fma_f32 v98, -v98, v139, v136
	v_div_fmas_f32 v136, v98, v137, v139
	v_div_fixup_f32 v71, v136, v99, v71
	v_cvt_pk_bf16_f32 v71, v71, v177
	global_store_short v[236:237], v71, off offset:384
	s_waitcnt vmcnt(11)
	v_lshlrev_b32_e32 v98, 16, v78
	v_fma_f32 v71, v212, v98, v158
	v_lshlrev_b32_e32 v98, 16, v90
	v_lshlrev_b32_e32 v99, 16, v146
	v_cndmask_b32_e64 v98, 0, v98, s[42:43]
	v_cndmask_b32_e64 v99, 0, v99, s[44:45]
	v_fmac_f32_e32 v71, v170, v98
	v_fmac_f32_e32 v71, v224, v99
	v_mul_f32_e32 v98, 0xbfb8aa3b, v71
	v_exp_f32_e32 v98, v98
	s_nop 0
	v_add_f32_e32 v99, 1.0, v98
	v_div_scale_f32 v98, s[52:53], v99, v99, v71
	v_rcp_f32_e32 v137, v98
	v_div_scale_f32 v136, vcc, v71, v99, v71
	v_fma_f32 v139, -v98, v137, 1.0
	v_fmac_f32_e32 v137, v139, v137
	v_mul_f32_e32 v139, v136, v137
	v_fma_f32 v140, -v98, v139, v136
	v_fmac_f32_e32 v139, v140, v137
	v_fma_f32 v98, -v98, v139, v136
	v_div_fmas_f32 v136, v98, v137, v139
	v_div_fixup_f32 v71, v136, v99, v71
	v_cvt_pk_bf16_f32 v71, v71, v177
	global_store_short v[236:237], v71, off offset:512
	s_waitcnt vmcnt(11)
	v_lshlrev_b32_e32 v98, 16, v79
	v_fma_f32 v71, v213, v98, v159
	v_lshlrev_b32_e32 v98, 16, v91
	v_lshlrev_b32_e32 v99, 16, v147
	v_cndmask_b32_e64 v98, 0, v98, s[42:43]
	v_cndmask_b32_e64 v99, 0, v99, s[44:45]
	v_fmac_f32_e32 v71, v171, v98
	v_fmac_f32_e32 v71, v225, v99
	v_mul_f32_e32 v98, 0xbfb8aa3b, v71
	v_exp_f32_e32 v98, v98
	s_nop 0
	v_add_f32_e32 v99, 1.0, v98
	v_div_scale_f32 v98, s[52:53], v99, v99, v71
	v_rcp_f32_e32 v137, v98
	v_div_scale_f32 v136, vcc, v71, v99, v71
	v_fma_f32 v139, -v98, v137, 1.0
	v_fmac_f32_e32 v137, v139, v137
	v_mul_f32_e32 v139, v136, v137
	v_fma_f32 v140, -v98, v139, v136
	v_fmac_f32_e32 v139, v140, v137
	v_fma_f32 v98, -v98, v139, v136
	v_div_fmas_f32 v136, v98, v137, v139
	v_div_fixup_f32 v71, v136, v99, v71
	v_cvt_pk_bf16_f32 v71, v71, v177
	global_store_short v[236:237], v71, off offset:640
	s_waitcnt vmcnt(11)
; __device__ __forceinline__ float bf2f(bh v) { return __uint_as_float(((unsigned)v) << 16); }
; __device__ __forceinline__ bh f2bf(float f) { return (bh)(cvtpk(f, 0.f) & 0xffffu); }
; __device__ __forceinline__ float silu_f(float x) { return x / (1.f + __expf(-x)); }
; __device__ __forceinline__ void prep1_phase(const Params& p, int l, int L, bh* __restrict__ U, bh* __restrict__ kb, bh* __restrict__ xc, float* __restrict__ dtb, unsigned* __restrict__ bnd) {
;     ...
;       const bool hasL = pos > 0, hasR = pos < L - 1;
; #pragma unroll
;       for (int i = 0; i < 12; ++i) {
;         const int c = i * 64 + lane;
;         float a = cbias[c] + cw[768 + c] * bf2f(Ur[UC_XBC + c]);
;         if (hasL) a += cw[c] * bf2f(Ur[UC_XBC + c - UW]);
;         if (hasR) a += cw[2 * 768 + c] * bf2f(Ur[UC_XBC + c + UW]);
;         xc[(long)t * 768 + c] = f2bf(silu_f(a));
;       }
;     }
;     if (lane < 16) {
;       const float raw = bf2f(Ur[UC_DT + lane]) + dtbias[lane];
;       const float e = __builtin_amdgcn_exp2f(raw * LOG2E);
;       const float sp = e < 1.0e-3f ? e * (1.f - 0.5f * e) : __builtin_amdgcn_logf(1.f + e) * 0.6931471805599453f;
;       dtb[(long)t * 16 + lane] = raw > 20.f ? raw : sp;
;     }
	v_lshlrev_b32_e32 v98, 16, v80
	v_fma_f32 v71, v214, v98, v160
	v_lshlrev_b32_e32 v98, 16, v92
	v_lshlrev_b32_e32 v99, 16, v148
	v_cndmask_b32_e64 v98, 0, v98, s[42:43]
	v_cndmask_b32_e64 v99, 0, v99, s[44:45]
	v_fmac_f32_e32 v71, v172, v98
	v_fmac_f32_e32 v71, v226, v99
	v_mul_f32_e32 v98, 0xbfb8aa3b, v71
	v_exp_f32_e32 v98, v98
	s_nop 0
	v_add_f32_e32 v99, 1.0, v98
	v_div_scale_f32 v98, s[52:53], v99, v99, v71
	v_rcp_f32_e32 v137, v98
	v_div_scale_f32 v136, vcc, v71, v99, v71
	v_fma_f32 v139, -v98, v137, 1.0
	v_fmac_f32_e32 v137, v139, v137
	v_mul_f32_e32 v139, v136, v137
	v_fma_f32 v140, -v98, v139, v136
	v_fmac_f32_e32 v139, v140, v137
	v_fma_f32 v98, -v98, v139, v136
	v_div_fmas_f32 v136, v98, v137, v139
	v_div_fixup_f32 v71, v136, v99, v71
	v_cvt_pk_bf16_f32 v71, v71, v177
	global_store_short v[236:237], v71, off offset:768
	s_waitcnt vmcnt(11)
	v_lshlrev_b32_e32 v98, 16, v81
	v_fma_f32 v71, v215, v98, v161
	v_lshlrev_b32_e32 v98, 16, v93
	v_lshlrev_b32_e32 v99, 16, v149
	v_cndmask_b32_e64 v98, 0, v98, s[42:43]
	v_cndmask_b32_e64 v99, 0, v99, s[44:45]
	v_fmac_f32_e32 v71, v173, v98
	v_fmac_f32_e32 v71, v227, v99
	v_mul_f32_e32 v98, 0xbfb8aa3b, v71
	v_exp_f32_e32 v98, v98
	s_nop 0
	v_add_f32_e32 v99, 1.0, v98
	v_div_scale_f32 v98, s[52:53], v99, v99, v71
	v_rcp_f32_e32 v137, v98
	v_div_scale_f32 v136, vcc, v71, v99, v71
	v_fma_f32 v139, -v98, v137, 1.0
	v_fmac_f32_e32 v137, v139, v137
	v_mul_f32_e32 v139, v136, v137
	v_fma_f32 v140, -v98, v139, v136
	v_fmac_f32_e32 v139, v140, v137
	v_fma_f32 v98, -v98, v139, v136
	v_div_fmas_f32 v136, v98, v137, v139
	v_div_fixup_f32 v71, v136, v99, v71
	v_cvt_pk_bf16_f32 v71, v71, v177
	global_store_short v[236:237], v71, off offset:896
	s_waitcnt vmcnt(11)
	v_lshlrev_b32_e32 v98, 16, v82
	v_fma_f32 v71, v216, v98, v162
	v_lshlrev_b32_e32 v98, 16, v94
	v_lshlrev_b32_e32 v99, 16, v150
	v_cndmask_b32_e64 v98, 0, v98, s[42:43]
	v_cndmask_b32_e64 v99, 0, v99, s[44:45]
	v_fmac_f32_e32 v71, v174, v98
	v_fmac_f32_e32 v71, v228, v99
	v_mul_f32_e32 v98, 0xbfb8aa3b, v71
	v_exp_f32_e32 v98, v98
	s_nop 0
	v_add_f32_e32 v99, 1.0, v98
	v_div_scale_f32 v98, s[52:53], v99, v99, v71
	v_rcp_f32_e32 v137, v98
	v_div_scale_f32 v136, vcc, v71, v99, v71
	v_fma_f32 v139, -v98, v137, 1.0
	v_fmac_f32_e32 v137, v139, v137
	v_mul_f32_e32 v139, v136, v137
	v_fma_f32 v140, -v98, v139, v136
	v_fmac_f32_e32 v139, v140, v137
	v_fma_f32 v98, -v98, v139, v136
	v_div_fmas_f32 v136, v98, v137, v139
	v_div_fixup_f32 v71, v136, v99, v71
	v_cvt_pk_bf16_f32 v71, v71, v177
	global_store_short v[236:237], v71, off offset:1024
	s_waitcnt vmcnt(11)
	v_lshlrev_b32_e32 v98, 16, v83
	v_fma_f32 v71, v217, v98, v163
	v_lshlrev_b32_e32 v98, 16, v95
	v_lshlrev_b32_e32 v99, 16, v151
	v_cndmask_b32_e64 v98, 0, v98, s[42:43]
	v_cndmask_b32_e64 v99, 0, v99, s[44:45]
	v_fmac_f32_e32 v71, v175, v98
	v_fmac_f32_e32 v71, v229, v99
	v_mul_f32_e32 v98, 0xbfb8aa3b, v71
	v_exp_f32_e32 v98, v98
	s_nop 0
	v_add_f32_e32 v99, 1.0, v98
	v_div_scale_f32 v98, s[52:53], v99, v99, v71
	v_rcp_f32_e32 v137, v98
	v_div_scale_f32 v136, vcc, v71, v99, v71
	v_fma_f32 v139, -v98, v137, 1.0
	v_fmac_f32_e32 v137, v139, v137
	v_mul_f32_e32 v139, v136, v137
	v_fma_f32 v140, -v98, v139, v136
	v_fmac_f32_e32 v139, v140, v137
	v_fma_f32 v98, -v98, v139, v136
	v_div_fmas_f32 v136, v98, v137, v139
	v_div_fixup_f32 v71, v136, v99, v71
	v_cvt_pk_bf16_f32 v71, v71, v177
	global_store_short v[236:237], v71, off offset:1152
	s_waitcnt vmcnt(11)
	v_lshlrev_b32_e32 v98, 16, v84
	v_fma_f32 v71, v218, v98, v164
	v_lshlrev_b32_e32 v98, 16, v96
	v_lshlrev_b32_e32 v99, 16, v152
	v_cndmask_b32_e64 v98, 0, v98, s[42:43]
	v_cndmask_b32_e64 v99, 0, v99, s[44:45]
	v_fmac_f32_e32 v71, v206, v98
	v_fmac_f32_e32 v71, v230, v99
	v_mul_f32_e32 v98, 0xbfb8aa3b, v71
	v_exp_f32_e32 v98, v98
	s_nop 0
	v_add_f32_e32 v99, 1.0, v98
	v_div_scale_f32 v98, s[52:53], v99, v99, v71
	v_rcp_f32_e32 v137, v98
	v_div_scale_f32 v136, vcc, v71, v99, v71
	v_fma_f32 v139, -v98, v137, 1.0
	v_fmac_f32_e32 v137, v139, v137
	v_mul_f32_e32 v139, v136, v137
	v_fma_f32 v140, -v98, v139, v136
	v_fmac_f32_e32 v139, v140, v137
	v_fma_f32 v98, -v98, v139, v136
	v_div_fmas_f32 v136, v98, v137, v139
	v_div_fixup_f32 v71, v136, v99, v71
	v_cvt_pk_bf16_f32 v71, v71, v177
	global_store_short v[236:237], v71, off offset:1280
	s_waitcnt vmcnt(11)
	v_lshlrev_b32_e32 v98, 16, v85
	v_fma_f32 v71, v219, v98, v165
	v_lshlrev_b32_e32 v98, 16, v97
	v_lshlrev_b32_e32 v99, 16, v153
	v_cndmask_b32_e64 v98, 0, v98, s[42:43]
	v_cndmask_b32_e64 v99, 0, v99, s[44:45]
	v_fmac_f32_e32 v71, v207, v98
	v_fmac_f32_e32 v71, v231, v99
	v_mul_f32_e32 v98, 0xbfb8aa3b, v71
	v_exp_f32_e32 v98, v98
	s_nop 0
	v_add_f32_e32 v99, 1.0, v98
	v_div_scale_f32 v98, s[52:53], v99, v99, v71
	v_rcp_f32_e32 v137, v98
	v_div_scale_f32 v136, vcc, v71, v99, v71
	v_fma_f32 v139, -v98, v137, 1.0
	v_fmac_f32_e32 v137, v139, v137
	v_mul_f32_e32 v139, v136, v137
	v_fma_f32 v140, -v98, v139, v136
	v_fmac_f32_e32 v139, v140, v137
	v_fma_f32 v98, -v98, v139, v136
	v_div_fmas_f32 v136, v98, v137, v139
	v_div_fixup_f32 v71, v136, v99, v71
	v_cvt_pk_bf16_f32 v71, v71, v177
	global_store_short v[236:237], v71, off offset:1408
	s_and_saveexec_b64 s[42:43], s[0:1]
	s_cbranch_execz .LBB0_253
	v_add_co_u32_e32 v72, vcc, 0x1000, v72
	s_mov_b32 s33, 0x3a83126f
	s_nop 0
	v_addc_co_u32_e32 v73, vcc, 0, v73, vcc
	v_mov_b32_e32 v71, v186
	s_nop 0
	v_mov_b32_e32 v72, v187
	v_lshlrev_b32_e32 v71, 16, v71
	v_add_f32_e32 v71, v72, v71
	v_mul_f32_e32 v72, 0x3fb8aa3b, v71
	v_exp_f32_e32 v73, v72
	s_nop 0
	v_cmp_ngt_f32_e32 vcc, s33, v73
	s_and_saveexec_b64 s[44:45], vcc
	s_xor_b64 s[44:45], exec, s[44:45]
	v_add_f32_e32 v72, 1.0, v73
	v_log_f32_e32 v72, v72
	s_nop 0
	v_mul_f32_e32 v72, 0x3f317218, v72
	s_andn2_saveexec_b64 s[44:45], s[44:45]
	s_cbranch_execz .LBB0_252
	v_fma_f32 v72, v73, -0.5, 1.0
	v_mul_f32_e32 v72, v73, v72
	s_branch .LBB0_252

; __device__ __forceinline__ float bf2f(bh v) { return __uint_as_float(((unsigned)v) << 16); }
; __device__ __forceinline__ bh f2bf(float f) { return (bh)(cvtpk(f, 0.f) & 0xffffu); }
; __device__ __forceinline__ float silu_f(float x) { return x / (1.f + __expf(-x)); }
; __device__ __forceinline__ void ssd_out_item(const bh* __restrict__ xc, const bh* __restrict__ U, const float* __restrict__ dtb, ...
;     ...
;     const float dsk = dskip[h];
; #pragma unroll
;     for (int m = 0; m < 2; ++m)
; #pragma unroll
;       for (int n = 0; n < 2; ++n) {
;         const int pp = pc + n * 16 + fr;
;         const float gg = ng[h * 64 + pp];
; #pragma unroll
;         for (int jj = 0; jj < 4; ++jj) {
;           const int i = ir + m * 16 + fq * 4 + jj;
;           const long t = t0 + i;
;           const float xv = bf2f(XT[pp * XTS + i]);
;           const float y = acc[m][n][jj] + dsk * xv;
;           const float z = bf2f(U[t * UW + UC_Z + h * 64 + pp]);
;           const float v = y * silu_f(z);
;           ssq[m][jj] += v * v;
;           ys[t * 2048 + 1024 + h * 64 + pp] = f2bf(v * gg);
;         }
;       }
.LBB0_615:
	v_readlane_b32 s44, v254, 0
	v_readlane_b32 s45, v254, 1
	s_lshl_b64 s[42:43], s[44:45], 2
	v_readlane_b32 s33, v254, 18
	s_add_u32 s42, s33, s42
	v_readlane_b32 s33, v254, 19
	s_addc_u32 s43, s33, s43
	global_load_dword v132, v177, s[42:43]
	v_readlane_b32 s46, v254, 2
	v_readlane_b32 s47, v254, 3
	v_readlane_b32 s33, v255, 9
	v_readlane_b32 s46, v254, 20
	v_readlane_b32 s47, v254, 21
	v_or_b32_e32 v176, s33, v115
	s_lshl_b32 s44, s33, 1
	v_lshl_add_u64 v[148:149], v[82:83], 0, s[44:45]
	global_load_ushort v150, v[148:149], off
	v_lshl_add_u64 v[148:149], v[84:85], 0, s[44:45]
	global_load_ushort v151, v[148:149], off
	v_lshl_add_u64 v[148:149], v[86:87], 0, s[44:45]
	global_load_ushort v152, v[148:149], off
	v_lshl_add_u64 v[148:149], v[88:89], 0, s[44:45]
	global_load_ushort v153, v[148:149], off
	v_lshl_add_u64 v[148:149], v[82:83], 0, s[44:45]
	global_load_ushort v154, v[148:149], off offset:32
	v_lshl_add_u64 v[148:149], v[84:85], 0, s[44:45]
	global_load_ushort v155, v[148:149], off offset:32
	v_lshl_add_u64 v[148:149], v[86:87], 0, s[44:45]
	global_load_ushort v156, v[148:149], off offset:32
	v_lshl_add_u64 v[148:149], v[88:89], 0, s[44:45]
	global_load_ushort v157, v[148:149], off offset:32
	v_lshl_add_u64 v[148:149], v[90:91], 0, s[44:45]
	global_load_ushort v158, v[148:149], off
	v_lshl_add_u64 v[148:149], v[92:93], 0, s[44:45]
	global_load_ushort v159, v[148:149], off
	v_lshl_add_u64 v[148:149], v[94:95], 0, s[44:45]
	global_load_ushort v160, v[148:149], off
	v_lshl_add_u64 v[148:149], v[96:97], 0, s[44:45]
	global_load_ushort v161, v[148:149], off
	v_lshl_add_u64 v[148:149], v[90:91], 0, s[44:45]
	global_load_ushort v162, v[148:149], off offset:32
	v_lshl_add_u64 v[148:149], v[92:93], 0, s[44:45]
	global_load_ushort v163, v[148:149], off offset:32
	v_lshl_add_u64 v[148:149], v[96:97], 0, s[44:45]
	global_load_ushort v164, v[148:149], off offset:32
	v_lshl_add_u64 v[148:149], v[94:95], 0, s[44:45]
	global_load_ushort v165, v[148:149], off offset:32
	v_lshl_add_u64 v[48:49], v[176:177], 2, s[46:47]
	global_load_dword v133, v[48:49], off
	ds_read_u16 v50, v125 offset:40960
	ds_read_u16 v54, v125 offset:40962
	ds_read_u16 v131, v125 offset:40964
	ds_read_u16 v136, v125 offset:40966
	v_lshl_add_u64 v[52:53], v[82:83], 0, s[44:45]
	s_waitcnt lgkmcnt(3)
	v_lshlrev_b32_e32 v50, 16, v50
	v_lshl_add_u64 v[48:49], v[80:81], 0, s[44:45]
	s_waitcnt lgkmcnt(1)
	v_lshlrev_b32_e32 v131, 16, v131
	v_add_u32_e32 v176, s33, v115
	v_readlane_b32 s48, v254, 4
	v_readlane_b32 s49, v254, 5
	v_readlane_b32 s50, v254, 6
	v_readlane_b32 s51, v254, 7
	v_readlane_b32 s52, v254, 8
	v_readlane_b32 s53, v254, 9
	v_readlane_b32 s54, v254, 10
	v_readlane_b32 s55, v254, 11
	v_readlane_b32 s56, v254, 12
	v_readlane_b32 s57, v254, 13
	v_readlane_b32 s58, v254, 14
	v_readlane_b32 s59, v254, 15
	s_waitcnt vmcnt(17)
	v_fma_f32 v44, v132, v50, v44
	s_waitcnt vmcnt(0)
	v_mov_b32_e32 v50, v150
	v_fma_f32 v46, v132, v131, v46
	s_waitcnt vmcnt(0)
	v_lshlrev_b32_e32 v50, 16, v50
	v_mul_f32_e32 v51, 0xbfb8aa3b, v50
	v_exp_f32_e32 v51, v51
	s_nop 0
	v_add_f32_e32 v51, 1.0, v51
	v_div_scale_f32 v55, s[42:43], v51, v51, v50
	v_rcp_f32_e32 v102, v55
	s_nop 0
	v_fma_f32 v103, -v55, v102, 1.0
	v_fmac_f32_e32 v102, v103, v102
	v_div_scale_f32 v103, vcc, v50, v51, v50
	v_mul_f32_e32 v134, v103, v102
	v_fma_f32 v135, -v55, v134, v103
	v_fmac_f32_e32 v134, v135, v102
	v_fma_f32 v55, -v55, v134, v103
	v_div_fmas_f32 v55, v55, v102, v134
	v_div_fixup_f32 v50, v55, v51, v50
	v_mul_f32_e32 v55, v44, v50
	v_mul_f32_e32 v44, v133, v55
	v_cvt_pk_bf16_f32 v44, v44, v177
	v_lshl_add_u64 v[50:51], v[48:49], 0, v[60:61]
	global_store_short v[50:51], v44, off offset:2048
	v_lshlrev_b32_e32 v44, 16, v54
	v_lshl_add_u64 v[102:103], v[84:85], 0, s[44:45]
	v_fma_f32 v44, v132, v44, v45
	v_mov_b32_e32 v45, v151
	v_lshlrev_b32_e32 v45, 16, v45
	v_mul_f32_e32 v54, 0xbfb8aa3b, v45
	v_exp_f32_e32 v54, v54
	s_nop 0
	v_add_f32_e32 v54, 1.0, v54
	v_div_scale_f32 v134, s[42:43], v54, v54, v45
	v_rcp_f32_e32 v135, v134
	s_nop 0
	v_fma_f32 v137, -v134, v135, 1.0
	v_fmac_f32_e32 v135, v137, v135
	v_div_scale_f32 v137, vcc, v45, v54, v45
	v_mul_f32_e32 v138, v137, v135
	v_fma_f32 v139, -v134, v138, v137
	v_fmac_f32_e32 v138, v139, v135
	v_fma_f32 v134, -v134, v138, v137
	v_div_fmas_f32 v134, v134, v135, v138
	v_div_fixup_f32 v45, v134, v54, v45
	v_mul_f32_e32 v54, v44, v45
	v_mul_f32_e32 v44, v133, v54
	v_cvt_pk_bf16_f32 v134, v44, v177
	v_lshl_add_u64 v[44:45], v[48:49], 0, v[64:65]
	global_store_short v[44:45], v134, off offset:2048
	v_lshl_add_u64 v[134:135], v[86:87], 0, s[44:45]
	v_mov_b32_e32 v131, v152
	v_lshlrev_b32_e32 v131, 16, v131
	v_mul_f32_e32 v137, 0xbfb8aa3b, v131
	v_exp_f32_e32 v137, v137
	s_nop 0
	v_add_f32_e32 v137, 1.0, v137
	v_div_scale_f32 v138, s[42:43], v137, v137, v131
	v_rcp_f32_e32 v139, v138
	s_nop 0
	v_fma_f32 v140, -v138, v139, 1.0
	v_fmac_f32_e32 v139, v140, v139
	v_div_scale_f32 v140, vcc, v131, v137, v131
	v_mul_f32_e32 v141, v140, v139
	v_fma_f32 v142, -v138, v141, v140
	v_fmac_f32_e32 v141, v142, v139
	v_fma_f32 v138, -v138, v141, v140
	v_div_fmas_f32 v138, v138, v139, v141
	v_div_fixup_f32 v131, v138, v137, v131
	v_mul_f32_e32 v137, v46, v131
	v_mul_f32_e32 v46, v133, v137
	v_cvt_pk_bf16_f32 v46, v46, v177
	v_lshl_add_u64 v[138:139], v[48:49], 0, v[66:67]
	global_store_short v[138:139], v46, off offset:2048
	s_waitcnt lgkmcnt(0)
; __device__ __forceinline__ float bf2f(bh v) { return __uint_as_float(((unsigned)v) << 16); }
; __device__ __forceinline__ bh f2bf(float f) { return (bh)(cvtpk(f, 0.f) & 0xffffu); }
; __device__ __forceinline__ float silu_f(float x) { return x / (1.f + __expf(-x)); }
; __device__ __forceinline__ void ssd_out_item(const bh* __restrict__ xc, const bh* __restrict__ U, const float* __restrict__ dtb, ...
;     ...
;     const float dsk = dskip[h];
; #pragma unroll
;     for (int m = 0; m < 2; ++m)
; #pragma unroll
;       for (int n = 0; n < 2; ++n) {
;         const int pp = pc + n * 16 + fr;
;         const float gg = ng[h * 64 + pp];
; #pragma unroll
;         for (int jj = 0; jj < 4; ++jj) {
;           const int i = ir + m * 16 + fq * 4 + jj;
;           const long t = t0 + i;
;           const float xv = bf2f(XT[pp * XTS + i]);
;           const float y = acc[m][n][jj] + dsk * xv;
;           const float z = bf2f(U[t * UW + UC_Z + h * 64 + pp]);
;           const float v = y * silu_f(z);
;           ssq[m][jj] += v * v;
;           ys[t * 2048 + 1024 + h * 64 + pp] = f2bf(v * gg);
;         }
;       }
	v_lshlrev_b32_e32 v46, 16, v136
	v_lshl_add_u64 v[140:141], v[88:89], 0, s[44:45]
	v_fmac_f32_e32 v47, v132, v46
	v_mov_b32_e32 v46, v153
	v_lshlrev_b32_e32 v46, 16, v46
	v_mul_f32_e32 v131, 0xbfb8aa3b, v46
	v_exp_f32_e32 v131, v131
	s_nop 0
	v_add_f32_e32 v131, 1.0, v131
	v_div_scale_f32 v136, s[42:43], v131, v131, v46
	v_rcp_f32_e32 v142, v136
	s_nop 0
	v_fma_f32 v143, -v136, v142, 1.0
	v_fmac_f32_e32 v142, v143, v142
	v_div_scale_f32 v143, vcc, v46, v131, v46
	v_mul_f32_e32 v144, v143, v142
	v_fma_f32 v145, -v136, v144, v143
	v_fmac_f32_e32 v144, v145, v142
	v_fma_f32 v136, -v136, v144, v143
	v_div_fmas_f32 v136, v136, v142, v144
	v_div_fixup_f32 v46, v136, v131, v46
	v_mul_f32_e32 v136, v47, v46
	v_mul_f32_e32 v46, v133, v136
	v_cvt_pk_bf16_f32 v131, v46, v177
	v_lshl_add_u64 v[46:47], v[48:49], 0, v[68:69]
	global_store_short v[46:47], v131, off offset:2048
	v_lshl_add_u64 v[142:143], v[176:177], 2, s[46:47]
	global_load_dword v131, v[142:143], off offset:64
	ds_read_u16 v142, v122 offset:40960
	ds_read_u16 v143, v122 offset:40962
	v_mov_b32_e32 v52, v154
	v_readlane_b32 s47, v255, 10
	s_add_i32 s47, s47, 1
	s_waitcnt lgkmcnt(1)
	v_lshlrev_b32_e32 v142, 16, v142
	v_fma_f32 v40, v132, v142, v40
	s_cmp_eq_u32 s47, 4
	s_waitcnt vmcnt(0)
	v_lshlrev_b32_e32 v52, 16, v52
	v_mul_f32_e32 v53, 0xbfb8aa3b, v52
	v_exp_f32_e32 v53, v53
	s_nop 0
	v_add_f32_e32 v53, 1.0, v53
	v_div_scale_f32 v142, s[42:43], v53, v53, v52
	v_rcp_f32_e32 v144, v142
	s_nop 0
	v_fma_f32 v145, -v142, v144, 1.0
	v_fmac_f32_e32 v144, v145, v144
	v_div_scale_f32 v145, vcc, v52, v53, v52
	v_mul_f32_e32 v146, v145, v144
	v_fma_f32 v147, -v142, v146, v145
	v_fmac_f32_e32 v146, v147, v144
	v_fma_f32 v142, -v142, v146, v145
	v_div_fmas_f32 v142, v142, v144, v146
	v_div_fixup_f32 v142, v142, v53, v52
	v_pk_fma_f32 v[52:53], v[54:55], v[54:55], v[98:99]
	s_waitcnt lgkmcnt(0)
	v_lshlrev_b32_e32 v54, 16, v143
	v_fma_f32 v41, v132, v54, v41
	v_mov_b32_e32 v54, v155
	v_mul_f32_e32 v55, v40, v142
	v_mul_f32_e32 v40, v131, v55
	v_cvt_pk_bf16_f32 v40, v40, v177
	global_store_short v[50:51], v40, off offset:2080
	v_lshlrev_b32_e32 v54, 16, v54
	v_mul_f32_e32 v98, 0xbfb8aa3b, v54
	v_exp_f32_e32 v98, v98
	s_nop 0
	v_add_f32_e32 v98, 1.0, v98
	v_div_scale_f32 v99, s[42:43], v98, v98, v54
	v_rcp_f32_e32 v102, v99
	s_nop 0
	v_fma_f32 v103, -v99, v102, 1.0
	v_fmac_f32_e32 v102, v103, v102
	v_div_scale_f32 v103, vcc, v54, v98, v54
	v_mul_f32_e32 v142, v103, v102
	v_fma_f32 v143, -v99, v142, v103
	v_fmac_f32_e32 v142, v143, v102
	v_fma_f32 v99, -v99, v142, v103
	v_div_fmas_f32 v99, v99, v102, v142
	v_div_fixup_f32 v54, v99, v98, v54
	v_mul_f32_e32 v54, v41, v54
	v_mul_f32_e32 v40, v131, v54
	v_cvt_pk_bf16_f32 v40, v40, v177
	global_store_short v[44:45], v40, off offset:2080
	ds_read_u16 v40, v122 offset:40964
	ds_read_u16 v44, v122 offset:40966
	v_pk_fma_f32 v[98:99], v[54:55], v[54:55], v[52:53]
	v_lshl_add_u64 v[102:103], v[92:93], 0, s[44:45]
	s_waitcnt lgkmcnt(1)
	v_lshlrev_b32_e32 v40, 16, v40
	v_fma_f32 v42, v132, v40, v42
	v_mov_b32_e32 v40, v156
	s_waitcnt lgkmcnt(0)
	v_lshlrev_b32_e32 v44, 16, v44
	v_fmac_f32_e32 v43, v132, v44
	v_mov_b32_e32 v44, v157
	v_lshlrev_b32_e32 v40, 16, v40
	v_mul_f32_e32 v41, 0xbfb8aa3b, v40
	v_exp_f32_e32 v41, v41
	v_lshlrev_b32_e32 v44, 16, v44
	v_add_f32_e32 v41, 1.0, v41
	v_div_scale_f32 v45, s[42:43], v41, v41, v40
	v_rcp_f32_e32 v50, v45
	s_nop 0
	v_fma_f32 v51, -v45, v50, 1.0
	v_fmac_f32_e32 v50, v51, v50
	v_div_scale_f32 v51, vcc, v40, v41, v40
	v_mul_f32_e32 v52, v51, v50
	v_fma_f32 v53, -v45, v52, v51
	v_fmac_f32_e32 v52, v53, v50
	v_fma_f32 v45, -v45, v52, v51
	v_div_fmas_f32 v45, v45, v50, v52
	v_mul_f32_e32 v50, 0xbfb8aa3b, v44
	v_exp_f32_e32 v50, v50
	v_div_fixup_f32 v45, v45, v41, v40
	v_pk_fma_f32 v[40:41], v[136:137], v[136:137], v[78:79]
	v_mul_f32_e32 v45, v42, v45
	v_add_f32_e32 v50, 1.0, v50
	v_div_scale_f32 v51, s[42:43], v50, v50, v44
	v_rcp_f32_e32 v52, v51
	v_mul_f32_e32 v42, v131, v45
	v_cvt_pk_bf16_f32 v42, v42, v177
	global_store_short v[138:139], v42, off offset:2080
	v_fma_f32 v53, -v51, v52, 1.0
	v_fmac_f32_e32 v52, v53, v52
	v_div_scale_f32 v53, vcc, v44, v50, v44
	v_mul_f32_e32 v54, v53, v52
	v_fma_f32 v55, -v51, v54, v53
	v_fmac_f32_e32 v54, v55, v52
	v_fma_f32 v51, -v51, v54, v53
	v_div_fmas_f32 v51, v51, v52, v54
	v_div_fixup_f32 v44, v51, v50, v44
	v_mul_f32_e32 v44, v43, v44
	v_pk_fma_f32 v[78:79], v[44:45], v[44:45], v[40:41]
	v_mul_f32_e32 v40, v131, v44
	v_cvt_pk_bf16_f32 v40, v40, v177
	global_store_short v[46:47], v40, off offset:2080
	ds_read_u16 v40, v125 offset:40992
	v_lshl_add_u64 v[44:45], v[90:91], 0, s[44:45]
	v_lshl_add_u64 v[54:55], v[48:49], 0, v[70:71]
	s_waitcnt lgkmcnt(0)
	v_lshlrev_b32_e32 v40, 16, v40
	v_fma_f32 v36, v132, v40, v36
	v_mov_b32_e32 v40, v158
	v_lshlrev_b32_e32 v40, 16, v40
	v_mul_f32_e32 v41, 0xbfb8aa3b, v40
	v_exp_f32_e32 v41, v41
	s_nop 0
	v_add_f32_e32 v41, 1.0, v41
	v_div_scale_f32 v42, s[42:43], v41, v41, v40
	v_rcp_f32_e32 v43, v42
	s_nop 0
	v_fma_f32 v46, -v42, v43, 1.0
	v_fmac_f32_e32 v43, v46, v43
	v_div_scale_f32 v46, vcc, v40, v41, v40
	v_mul_f32_e32 v47, v46, v43
	v_fma_f32 v50, -v42, v47, v46
	v_fmac_f32_e32 v47, v50, v43
	v_fma_f32 v42, -v42, v47, v46
	v_div_fmas_f32 v42, v42, v43, v47
	v_div_fixup_f32 v40, v42, v41, v40
	v_mul_f32_e32 v47, v36, v40
	v_mul_f32_e32 v36, v133, v47
	v_cvt_pk_bf16_f32 v36, v36, v177
	v_lshl_add_u64 v[42:43], v[48:49], 0, v[62:63]
	global_store_short v[42:43], v36, off offset:2048
	ds_read_u16 v36, v125 offset:40994
	s_waitcnt lgkmcnt(0)
; __device__ __forceinline__ float bf2f(bh v) { return __uint_as_float(((unsigned)v) << 16); }
; __device__ __forceinline__ bh f2bf(float f) { return (bh)(cvtpk(f, 0.f) & 0xffffu); }
; __device__ __forceinline__ float silu_f(float x) { return x / (1.f + __expf(-x)); }
; __device__ __forceinline__ void ssd_out_item(const bh* __restrict__ xc, const bh* __restrict__ U, const float* __restrict__ dtb, ...
;     ...
;     const float dsk = dskip[h];
; #pragma unroll
;     for (int m = 0; m < 2; ++m)
; #pragma unroll
;       for (int n = 0; n < 2; ++n) {
;         const int pp = pc + n * 16 + fr;
;         const float gg = ng[h * 64 + pp];
; #pragma unroll
;         for (int jj = 0; jj < 4; ++jj) {
;           const int i = ir + m * 16 + fq * 4 + jj;
;           const long t = t0 + i;
;           const float xv = bf2f(XT[pp * XTS + i]);
;           const float y = acc[m][n][jj] + dsk * xv;
;           const float z = bf2f(U[t * UW + UC_Z + h * 64 + pp]);
;           const float v = y * silu_f(z);
;           ssq[m][jj] += v * v;
;           ys[t * 2048 + 1024 + h * 64 + pp] = f2bf(v * gg);
;         }
;       }
;     __syncthreads();
;   }
; #pragma unroll
;   for (int m = 0; m < 2; ++m)
; #pragma unroll
;     for (int jj = 0; jj < 4; ++jj) {
;       float v = ssq[m][jj];
;       v = row16_sum(v);
;       if (fr == 0) rs_s[(ir + m * 16 + fq * 4 + jj) * 2 + (wid & 1)] = v;
;     }
;   __syncthreads();
;   if (tid < 128) ssp[(long)(t0 + tid) * 2 + g] = rs_s[tid * 2] + rs_s[tid * 2 + 1];
	v_lshlrev_b32_e32 v36, 16, v36
	v_fma_f32 v36, v132, v36, v37
	v_mov_b32_e32 v37, v159
	v_lshlrev_b32_e32 v37, 16, v37
	v_mul_f32_e32 v40, 0xbfb8aa3b, v37
	v_exp_f32_e32 v40, v40
	s_nop 0
	v_add_f32_e32 v40, 1.0, v40
	v_div_scale_f32 v41, s[42:43], v40, v40, v37
	v_rcp_f32_e32 v46, v41
	s_nop 0
	v_fma_f32 v50, -v41, v46, 1.0
	v_fmac_f32_e32 v46, v50, v46
	v_div_scale_f32 v50, vcc, v37, v40, v37
	v_mul_f32_e32 v51, v50, v46
	v_fma_f32 v52, -v41, v51, v50
	v_fmac_f32_e32 v51, v52, v46
	v_fma_f32 v41, -v41, v51, v50
	v_div_fmas_f32 v41, v41, v46, v51
	v_div_fixup_f32 v37, v41, v40, v37
	v_lshl_add_u64 v[50:51], v[94:95], 0, s[44:45]
	v_mul_f32_e32 v46, v36, v37
	v_mov_b32_e32 v37, v160
	v_mul_f32_e32 v36, v133, v46
	v_cvt_pk_bf16_f32 v36, v36, v177
	global_store_short v[54:55], v36, off offset:2048
	ds_read_u16 v36, v125 offset:40996
	s_waitcnt lgkmcnt(0)
	v_lshlrev_b32_e32 v36, 16, v36
	v_fma_f32 v36, v132, v36, v38
	v_lshlrev_b32_e32 v37, 16, v37
	v_mul_f32_e32 v38, 0xbfb8aa3b, v37
	v_exp_f32_e32 v38, v38
	s_nop 0
	v_add_f32_e32 v38, 1.0, v38
	v_div_scale_f32 v40, s[42:43], v38, v38, v37
	v_rcp_f32_e32 v41, v40
	s_nop 0
	v_fma_f32 v52, -v40, v41, 1.0
	v_fmac_f32_e32 v41, v52, v41
	v_div_scale_f32 v52, vcc, v37, v38, v37
	v_mul_f32_e32 v53, v52, v41
	v_fma_f32 v134, -v40, v53, v52
	v_fmac_f32_e32 v53, v134, v41
	v_fma_f32 v40, -v40, v53, v52
	v_div_fmas_f32 v40, v40, v41, v53
	v_div_fixup_f32 v37, v40, v38, v37
	v_mul_f32_e32 v53, v36, v37
	v_mul_f32_e32 v36, v133, v53
	v_cvt_pk_bf16_f32 v38, v36, v177
	v_lshl_add_u64 v[36:37], v[48:49], 0, v[72:73]
	global_store_short v[36:37], v38, off offset:2048
	ds_read_u16 v38, v125 offset:40998
	v_lshl_add_u64 v[40:41], v[96:97], 0, s[44:45]
	s_waitcnt lgkmcnt(0)
	v_lshlrev_b32_e32 v38, 16, v38
	v_fmac_f32_e32 v39, v132, v38
	v_mov_b32_e32 v38, v161
	v_lshlrev_b32_e32 v38, 16, v38
	v_mul_f32_e32 v52, 0xbfb8aa3b, v38
	v_exp_f32_e32 v52, v52
	s_nop 0
	v_add_f32_e32 v52, 1.0, v52
	v_div_scale_f32 v134, s[42:43], v52, v52, v38
	v_rcp_f32_e32 v135, v134
	s_nop 0
	v_fma_f32 v136, -v134, v135, 1.0
	v_fmac_f32_e32 v135, v136, v135
	v_div_scale_f32 v136, vcc, v38, v52, v38
	v_mul_f32_e32 v137, v136, v135
	v_fma_f32 v138, -v134, v137, v136
	v_fmac_f32_e32 v137, v138, v135
	v_fma_f32 v134, -v134, v137, v136
	v_div_fmas_f32 v134, v134, v135, v137
	v_div_fixup_f32 v38, v134, v52, v38
	v_mul_f32_e32 v52, v39, v38
	v_mul_f32_e32 v38, v133, v52
	v_cvt_pk_bf16_f32 v133, v38, v177
	v_lshl_add_u64 v[38:39], v[48:49], 0, v[74:75]
	global_store_short v[38:39], v133, off offset:2048
	ds_read_u16 v48, v122 offset:40992
	ds_read_u16 v49, v122 offset:40994
	v_mov_b32_e32 v44, v162
	s_waitcnt lgkmcnt(1)
	v_lshlrev_b32_e32 v48, 16, v48
	v_fma_f32 v32, v132, v48, v32
	v_lshlrev_b32_e32 v44, 16, v44
	v_mul_f32_e32 v45, 0xbfb8aa3b, v44
	v_exp_f32_e32 v45, v45
	s_nop 0
	v_add_f32_e32 v45, 1.0, v45
	v_div_scale_f32 v48, s[42:43], v45, v45, v44
	v_rcp_f32_e32 v133, v48
	s_nop 0
	v_fma_f32 v134, -v48, v133, 1.0
	v_fmac_f32_e32 v133, v134, v133
	v_div_scale_f32 v134, vcc, v44, v45, v44
	v_mul_f32_e32 v135, v134, v133
	v_fma_f32 v136, -v48, v135, v134
	v_fmac_f32_e32 v135, v136, v133
	v_fma_f32 v48, -v48, v135, v134
	v_div_fmas_f32 v48, v48, v133, v135
	v_div_fixup_f32 v48, v48, v45, v44
	v_pk_fma_f32 v[44:45], v[46:47], v[46:47], v[76:77]
	s_waitcnt lgkmcnt(0)
	v_lshlrev_b32_e32 v46, 16, v49
	v_fma_f32 v33, v132, v46, v33
	v_mov_b32_e32 v46, v163
	v_mul_f32_e32 v47, v32, v48
	v_mul_f32_e32 v32, v131, v47
	v_cvt_pk_bf16_f32 v32, v32, v177
	global_store_short v[42:43], v32, off offset:2080
	v_lshlrev_b32_e32 v46, 16, v46
	v_mul_f32_e32 v48, 0xbfb8aa3b, v46
	v_exp_f32_e32 v48, v48
	s_nop 0
	v_add_f32_e32 v48, 1.0, v48
	v_div_scale_f32 v49, s[42:43], v48, v48, v46
	v_rcp_f32_e32 v76, v49
	s_nop 0
	v_fma_f32 v77, -v49, v76, 1.0
	v_fmac_f32_e32 v76, v77, v76
	v_div_scale_f32 v77, vcc, v46, v48, v46
	v_mul_f32_e32 v102, v77, v76
	v_fma_f32 v103, -v49, v102, v77
	v_fmac_f32_e32 v102, v103, v76
	v_fma_f32 v49, -v49, v102, v77
	v_div_fmas_f32 v49, v49, v76, v102
	v_div_fixup_f32 v46, v49, v48, v46
	v_mul_f32_e32 v46, v33, v46
	v_mul_f32_e32 v32, v131, v46
	v_cvt_pk_bf16_f32 v32, v32, v177
	global_store_short v[54:55], v32, off offset:2080
	ds_read_u16 v32, v122 offset:40996
	ds_read_u16 v42, v122 offset:40998
	v_mov_b32_e32 v40, v164
	v_pk_fma_f32 v[76:77], v[46:47], v[46:47], v[44:45]
	s_waitcnt lgkmcnt(1)
	v_lshlrev_b32_e32 v32, 16, v32
	v_fma_f32 v34, v132, v32, v34
	v_mov_b32_e32 v32, v165
	s_waitcnt lgkmcnt(0)
	v_lshlrev_b32_e32 v42, 16, v42
	v_fmac_f32_e32 v35, v132, v42
	v_lshlrev_b32_e32 v40, 16, v40
	v_mul_f32_e32 v41, 0xbfb8aa3b, v40
	v_exp_f32_e32 v41, v41
	v_lshlrev_b32_e32 v32, 16, v32
	v_mul_f32_e32 v33, 0xbfb8aa3b, v32
	v_exp_f32_e32 v33, v33
	v_add_f32_e32 v41, 1.0, v41
	v_div_scale_f32 v42, s[42:43], v41, v41, v40
	v_add_f32_e32 v33, 1.0, v33
	v_div_scale_f32 v43, s[42:43], v33, v33, v32
	v_rcp_f32_e32 v44, v43
	s_nop 0
	v_fma_f32 v45, -v43, v44, 1.0
	v_fmac_f32_e32 v44, v45, v44
	v_div_scale_f32 v45, vcc, v32, v33, v32
	v_mul_f32_e32 v46, v45, v44
	v_fma_f32 v47, -v43, v46, v45
	v_fmac_f32_e32 v46, v47, v44
	v_fma_f32 v43, -v43, v46, v45
	v_div_fmas_f32 v43, v43, v44, v46
	v_rcp_f32_e32 v44, v42
	v_div_fixup_f32 v43, v43, v33, v32
	v_pk_fma_f32 v[32:33], v[52:53], v[52:53], v[100:101]
	v_mul_f32_e32 v43, v34, v43
	v_fma_f32 v45, -v42, v44, 1.0
	v_fmac_f32_e32 v44, v45, v44
	v_div_scale_f32 v45, vcc, v40, v41, v40
	v_mul_f32_e32 v46, v45, v44
	v_fma_f32 v47, -v42, v46, v45
	v_fmac_f32_e32 v46, v47, v44
	v_fma_f32 v42, -v42, v46, v45
	v_div_fmas_f32 v42, v42, v44, v46
	v_div_fixup_f32 v40, v42, v41, v40
	v_mul_f32_e32 v42, v35, v40
	v_mul_f32_e32 v34, v131, v43
	v_pk_fma_f32 v[100:101], v[42:43], v[42:43], v[32:33]
	v_mul_f32_e32 v32, v131, v42
	v_cvt_pk_bf16_f32 v34, v34, v177
	global_store_short v[36:37], v34, off offset:2080
	v_cvt_pk_bf16_f32 v32, v32, v177
	global_store_short v[38:39], v32, off offset:2080
	s_barrier
	s_cbranch_scc1 .LBB0_682

; __device__ __forceinline__ void merge_phase(const bh* __restrict__ ys, const bh* __restrict__ G, const bh* __restrict__ Wb,
;                             const float* __restrict__ ssp, bh* __restrict__ merged, char* lds) {
;     ...
;       for (int hf = 0; hf < 2; ++hf) {
; #pragma unroll
;         for (int i = 0; i < 4; ++i) {
;           const int id = tid + 512 * (hf * 4 + i), r = id >> 4, c8 = (id & 15) * 8;
;           *reinterpret_cast<bf16x8*>(gs + r * 136 + c8) =
;               *reinterpret_cast<const bf16x8*>(G + (long)(tm * 256 + r) * 4096 + n * 1024 + tn * 128 + c8);
;         }
;         asm volatile("" ::: "memory");
;       }
;       if (tid < 256) {
;         float scv = 1.f;
;         if (n == 2) { const int row = tm * 256 + tid; scv = rsqrtf((ssp[row * 2] + ssp[row * 2 + 1]) * (1.f / 512.f) + EPS); }
;         scs[tid] = scv;
;       }
.LBB0_800:
	v_lshl_add_u64 v[228:229], s[48:49], 1, v[138:139]
	v_lshl_add_u64 v[230:231], v[228:229], 0, v[144:145]
	global_load_dwordx4 v[64:67], v[230:231], off
	v_lshl_add_u64 v[230:231], v[228:229], 0, v[148:149]
	global_load_dwordx4 v[68:71], v[230:231], off
	v_lshl_add_u64 v[230:231], v[228:229], 0, v[150:151]
	global_load_dwordx4 v[72:75], v[230:231], off
	v_lshl_add_u64 v[230:231], v[228:229], 0, v[152:153]
	global_load_dwordx4 v[76:79], v[230:231], off
	v_lshl_add_u64 v[230:231], v[228:229], 0, v[154:155]
	global_load_dwordx4 v[80:83], v[230:231], off
	v_lshl_add_u64 v[230:231], v[228:229], 0, v[158:159]
	global_load_dwordx4 v[84:87], v[230:231], off
	v_lshl_add_u64 v[230:231], v[228:229], 0, v[162:163]
	global_load_dwordx4 v[232:235], v[230:231], off
	v_lshl_add_u64 v[230:231], v[228:229], 0, v[164:165]
	global_load_dwordx4 v[236:239], v[230:231], off
	s_waitcnt vmcnt(7)
	ds_write_b128 v214, v[64:67]
	s_waitcnt vmcnt(6)
	ds_write_b128 v215, v[68:71]
	s_waitcnt vmcnt(5)
	ds_write_b128 v216, v[72:75]
	s_waitcnt vmcnt(4)
	ds_write_b128 v217, v[76:79]
	s_waitcnt vmcnt(3)
	ds_write_b128 v218, v[80:83]
	s_waitcnt vmcnt(2)
	ds_write_b128 v219, v[84:87]
	s_waitcnt vmcnt(1)
	ds_write_b128 v220, v[232:235]
	s_waitcnt vmcnt(0)
	ds_write_b128 v221, v[236:239]
	s_and_saveexec_b64 s[8:9], s[0:1]
	s_cbranch_execz .LBB0_793
	s_cmp_lg_u32 s20, 2
	v_mov_b32_e32 v64, 1.0
	s_cbranch_scc1 .LBB0_792
	global_load_dwordx2 v[64:65], v[142:143], off
	s_waitcnt vmcnt(0)
	v_add_f32_e32 v64, v64, v65
	v_fmamk_f32 v64, v64, 0x3b000000, v189
	v_mul_f32_e32 v65, 0x4b800000, v64
	v_cmp_gt_f32_e32 vcc, s46, v64
	s_nop 1
	v_cndmask_b32_e32 v64, v64, v65, vcc
	v_rsq_f32_e32 v64, v64
	s_nop 0
	v_mul_f32_e32 v65, 0x45800000, v64
	v_cndmask_b32_e32 v64, v64, v65, vcc
	s_branch .LBB0_792
